# P0 weight-copy: gate items' 16 gain values loaded in one batch (were 8 dependent round trips per item), stacked on v78
# speedup vs baseline: 1.0033x; 1.0033x over previous
.LBB0_61:
	s_and_b64 vcc, exec, s[28:29]
	s_cbranch_vccz .LBB0_34
	s_mul_hi_i32 s2, s3, 0x2e8ba2e9
	s_lshr_b32 s8, s2, 31
	s_ashr_i32 s2, s2, 3
	s_add_i32 s2, s2, s8
	s_mul_i32 s8, s2, 0xfffff500
	s_add_i32 s28, s36, s8
	s_lshl_b32 s30, s2, 6
	v_or_b32_e32 v78, s30, v68
	s_ashr_i32 s29, s28, 31
	v_lshl_add_u64 v[2:3], s[28:29], 2, v[76:77]
	v_or_b32_e32 v6, 4, v78
	v_mad_i64_i32 v[4:5], s[34:35], v78, s42, v[2:3]
	v_mad_i64_i32 v[6:7], s[34:35], v6, s42, v[2:3]
	global_load_dwordx4 v[62:65], v[4:5], off nt
	global_load_dwordx4 v[58:61], v[6:7], off nt
	v_or_b32_e32 v4, 8, v78
	v_or_b32_e32 v6, 12, v78
	v_mad_i64_i32 v[4:5], s[34:35], v4, s42, v[2:3]
	v_mad_i64_i32 v[6:7], s[34:35], v6, s42, v[2:3]
	global_load_dwordx4 v[54:57], v[4:5], off nt
	global_load_dwordx4 v[50:53], v[6:7], off nt
	v_or_b32_e32 v4, 16, v78
	v_or_b32_e32 v6, 20, v78
	v_mad_i64_i32 v[4:5], s[34:35], v4, s42, v[2:3]
	v_mad_i64_i32 v[6:7], s[34:35], v6, s42, v[2:3]
	global_load_dwordx4 v[46:49], v[4:5], off nt
	global_load_dwordx4 v[42:45], v[6:7], off nt
	v_or_b32_e32 v4, 24, v78
	v_or_b32_e32 v6, 28, v78
	v_mad_i64_i32 v[4:5], s[34:35], v4, s42, v[2:3]
	v_mad_i64_i32 v[6:7], s[34:35], v6, s42, v[2:3]
	global_load_dwordx4 v[38:41], v[4:5], off nt
	global_load_dwordx4 v[34:37], v[6:7], off nt
	v_or_b32_e32 v4, 32, v78
	v_or_b32_e32 v6, 36, v78
	v_mad_i64_i32 v[4:5], s[34:35], v4, s42, v[2:3]
	v_mad_i64_i32 v[6:7], s[34:35], v6, s42, v[2:3]
	global_load_dwordx4 v[30:33], v[4:5], off nt
	global_load_dwordx4 v[26:29], v[6:7], off nt
	v_or_b32_e32 v4, 40, v78
	v_or_b32_e32 v6, 44, v78
	v_mad_i64_i32 v[4:5], s[34:35], v4, s42, v[2:3]
	v_mad_i64_i32 v[6:7], s[34:35], v6, s42, v[2:3]
	global_load_dwordx4 v[22:25], v[4:5], off nt
	global_load_dwordx4 v[18:21], v[6:7], off nt
	v_or_b32_e32 v4, 48, v78
	v_or_b32_e32 v6, 52, v78
	v_mad_i64_i32 v[4:5], s[34:35], v4, s42, v[2:3]
	v_mad_i64_i32 v[6:7], s[34:35], v6, s42, v[2:3]
	global_load_dwordx4 v[14:17], v[4:5], off nt
	global_load_dwordx4 v[10:13], v[6:7], off nt
	v_or_b32_e32 v4, 56, v78
	v_or_b32_e32 v6, 60, v78
	v_mad_i64_i32 v[4:5], s[34:35], v4, s42, v[2:3]
	v_mad_i64_i32 v[2:3], s[34:35], v6, s42, v[2:3]
	global_load_dwordx4 v[6:9], v[4:5], off nt
	s_nop 0
	global_load_dwordx4 v[2:5], v[2:3], off nt
	s_and_b64 vcc, exec, s[4:5]
	v_add_u32_e32 v105, v80, v81
	s_cbranch_vccnz .LBB0_93
	v_readlane_b32 s72, v254, 10
	v_ashrrev_i32_e32 v79, 31, v78
	v_readlane_b32 s82, v254, 20
	v_readlane_b32 s83, v254, 21
	s_ashr_i32 s31, s30, 31
	v_lshl_add_u64 v[106:107], s[30:31], 0, v[68:69]
	v_lshl_add_u64 v[78:79], v[78:79], 2, s[82:83]
	global_load_dword v78, v[78:79], off
	v_lshl_add_u64 v[106:107], v[106:107], 2, s[82:83]
	global_load_dword v70, v[106:107], off offset:16
	global_load_dword v220, v[106:107], off offset:32
	global_load_dword v221, v[106:107], off offset:48
	global_load_dword v222, v[106:107], off offset:64
	global_load_dword v223, v[106:107], off offset:80
	global_load_dword v224, v[106:107], off offset:96
	global_load_dword v225, v[106:107], off offset:112
	global_load_dword v226, v[106:107], off offset:128
	global_load_dword v227, v[106:107], off offset:144
	global_load_dword v228, v[106:107], off offset:160
	global_load_dword v229, v[106:107], off offset:176
	global_load_dword v230, v[106:107], off offset:192
	global_load_dword v231, v[106:107], off offset:208
	global_load_dword v232, v[106:107], off offset:224
	global_load_dword v233, v[106:107], off offset:240
	v_readlane_b32 s73, v254, 11
	v_readlane_b32 s74, v254, 12
	v_readlane_b32 s75, v254, 13
	v_readlane_b32 s76, v254, 14
	v_readlane_b32 s77, v254, 15
	v_readlane_b32 s78, v254, 16
	v_readlane_b32 s79, v254, 17
	v_readlane_b32 s80, v254, 18
	v_readlane_b32 s81, v254, 19
	v_readlane_b32 s84, v254, 22
	v_readlane_b32 s85, v254, 23
	v_readlane_b32 s86, v254, 24
	v_readlane_b32 s87, v254, 25
	s_waitcnt vmcnt(15)
	v_pk_mul_f32 v[106:107], v[62:63], v[78:79] op_sel_hi:[1,0]
	v_pk_mul_f32 v[78:79], v[64:65], v[78:79] op_sel_hi:[1,0]
	ds_write2_b32 v105, v106, v107 offset1:1
	ds_write2_b32 v105, v78, v79 offset0:2 offset1:3
	s_cbranch_execnz .LBB0_65

.LBB0_65:
	s_waitcnt vmcnt(14)
	v_pk_mul_f32 v[58:59], v[58:59], v[70:71] op_sel_hi:[1,0]
	v_add_u32_e32 v62, v80, v95
	ds_write2_b32 v62, v58, v59 offset1:1
	v_pk_mul_f32 v[58:59], v[60:61], v[70:71] op_sel_hi:[1,0]
	ds_write2_b32 v62, v58, v59 offset0:2 offset1:3
	s_and_b64 vcc, exec, s[4:5]
	v_add_u32_e32 v59, v80, v96
	s_cbranch_vccnz .LBB0_94
	s_ashr_i32 s31, s30, 31
	v_readlane_b32 s72, v254, 10
	v_lshl_add_u64 v[60:61], s[30:31], 0, v[68:69]
	v_readlane_b32 s82, v254, 20
	v_readlane_b32 s83, v254, 21
	v_readlane_b32 s73, v254, 11
	s_nop 0
	v_lshl_add_u64 v[60:61], v[60:61], 2, s[82:83]
	v_readlane_b32 s74, v254, 12
	v_readlane_b32 s75, v254, 13
	v_readlane_b32 s76, v254, 14
	v_readlane_b32 s77, v254, 15
	v_readlane_b32 s78, v254, 16
	v_readlane_b32 s79, v254, 17
	v_readlane_b32 s80, v254, 18
	v_readlane_b32 s81, v254, 19
	v_readlane_b32 s84, v254, 22
	v_readlane_b32 s85, v254, 23
	v_readlane_b32 s86, v254, 24
	v_readlane_b32 s87, v254, 25
	s_waitcnt vmcnt(12)
	v_mov_b32_e32 v62, v220
	v_mov_b32_e32 v58, v221
	v_pk_mul_f32 v[60:61], v[54:55], v[62:63] op_sel_hi:[1,0]
	v_pk_mul_f32 v[62:63], v[56:57], v[62:63] op_sel_hi:[1,0]
	ds_write2_b32 v59, v60, v61 offset1:1
	ds_write2_b32 v59, v62, v63 offset0:2 offset1:3
	s_cbranch_execnz .LBB0_68

.LBB0_68:
	s_waitcnt vmcnt(12)
	v_pk_mul_f32 v[50:51], v[50:51], v[58:59] op_sel_hi:[1,0]
	v_add_u32_e32 v54, v80, v97
	ds_write2_b32 v54, v50, v51 offset1:1
	v_pk_mul_f32 v[50:51], v[52:53], v[58:59] op_sel_hi:[1,0]
	ds_write2_b32 v54, v50, v51 offset0:2 offset1:3
	s_and_b64 vcc, exec, s[4:5]
	v_add_u32_e32 v51, v80, v98
	s_cbranch_vccnz .LBB0_95
	s_ashr_i32 s31, s30, 31
	v_readlane_b32 s72, v254, 10
	v_lshl_add_u64 v[52:53], s[30:31], 0, v[68:69]
	v_readlane_b32 s82, v254, 20
	v_readlane_b32 s83, v254, 21
	v_readlane_b32 s73, v254, 11
	s_nop 0
	v_lshl_add_u64 v[52:53], v[52:53], 2, s[82:83]
	v_readlane_b32 s74, v254, 12
	v_readlane_b32 s75, v254, 13
	v_readlane_b32 s76, v254, 14
	v_readlane_b32 s77, v254, 15
	v_readlane_b32 s78, v254, 16
	v_readlane_b32 s79, v254, 17
	v_readlane_b32 s80, v254, 18
	v_readlane_b32 s81, v254, 19
	v_readlane_b32 s84, v254, 22
	v_readlane_b32 s85, v254, 23
	v_readlane_b32 s86, v254, 24
	v_readlane_b32 s87, v254, 25
	s_waitcnt vmcnt(10)
	v_mov_b32_e32 v54, v222
	v_mov_b32_e32 v50, v223
	v_pk_mul_f32 v[52:53], v[46:47], v[54:55] op_sel_hi:[1,0]
	v_pk_mul_f32 v[54:55], v[48:49], v[54:55] op_sel_hi:[1,0]
	ds_write2_b32 v51, v52, v53 offset1:1
	ds_write2_b32 v51, v54, v55 offset0:2 offset1:3
	s_cbranch_execnz .LBB0_71

.LBB0_71:
	s_waitcnt vmcnt(10)
	v_pk_mul_f32 v[42:43], v[42:43], v[50:51] op_sel_hi:[1,0]
	v_add_u32_e32 v46, v80, v99
	ds_write2_b32 v46, v42, v43 offset1:1
	v_pk_mul_f32 v[42:43], v[44:45], v[50:51] op_sel_hi:[1,0]
	ds_write2_b32 v46, v42, v43 offset0:2 offset1:3
	s_and_b64 vcc, exec, s[4:5]
	v_add_u32_e32 v43, v80, v100
	s_cbranch_vccnz .LBB0_96
	s_ashr_i32 s31, s30, 31
	v_readlane_b32 s72, v254, 10
	v_lshl_add_u64 v[44:45], s[30:31], 0, v[68:69]
	v_readlane_b32 s82, v254, 20
	v_readlane_b32 s83, v254, 21
	v_readlane_b32 s73, v254, 11
	s_nop 0
	v_lshl_add_u64 v[44:45], v[44:45], 2, s[82:83]
	v_readlane_b32 s74, v254, 12
	v_readlane_b32 s75, v254, 13
	v_readlane_b32 s76, v254, 14
	v_readlane_b32 s77, v254, 15
	v_readlane_b32 s78, v254, 16
	v_readlane_b32 s79, v254, 17
	v_readlane_b32 s80, v254, 18
	v_readlane_b32 s81, v254, 19
	v_readlane_b32 s84, v254, 22
	v_readlane_b32 s85, v254, 23
	v_readlane_b32 s86, v254, 24
	v_readlane_b32 s87, v254, 25
	s_waitcnt vmcnt(8)
	v_mov_b32_e32 v46, v224
	v_mov_b32_e32 v42, v225
	v_pk_mul_f32 v[44:45], v[38:39], v[46:47] op_sel_hi:[1,0]
	v_pk_mul_f32 v[46:47], v[40:41], v[46:47] op_sel_hi:[1,0]
	ds_write2_b32 v43, v44, v45 offset1:1
	ds_write2_b32 v43, v46, v47 offset0:2 offset1:3
	s_cbranch_execnz .LBB0_74

.LBB0_74:
	s_waitcnt vmcnt(8)
	v_pk_mul_f32 v[34:35], v[34:35], v[42:43] op_sel_hi:[1,0]
	v_add_u32_e32 v38, v80, v101
	ds_write2_b32 v38, v34, v35 offset1:1
	v_pk_mul_f32 v[34:35], v[36:37], v[42:43] op_sel_hi:[1,0]
	ds_write2_b32 v38, v34, v35 offset0:2 offset1:3
	s_and_b64 vcc, exec, s[4:5]
	v_add_u32_e32 v35, v80, v102
	s_cbranch_vccnz .LBB0_97
	s_ashr_i32 s31, s30, 31
	v_readlane_b32 s72, v254, 10
	v_lshl_add_u64 v[36:37], s[30:31], 0, v[68:69]
	v_readlane_b32 s82, v254, 20
	v_readlane_b32 s83, v254, 21
	v_readlane_b32 s73, v254, 11
	s_nop 0
	v_lshl_add_u64 v[36:37], v[36:37], 2, s[82:83]
	v_readlane_b32 s74, v254, 12
	v_readlane_b32 s75, v254, 13
	v_readlane_b32 s76, v254, 14
	v_readlane_b32 s77, v254, 15
	v_readlane_b32 s78, v254, 16
	v_readlane_b32 s79, v254, 17
	v_readlane_b32 s80, v254, 18
	v_readlane_b32 s81, v254, 19
	v_readlane_b32 s84, v254, 22
	v_readlane_b32 s85, v254, 23
	v_readlane_b32 s86, v254, 24
	v_readlane_b32 s87, v254, 25
	s_waitcnt vmcnt(6)
	v_mov_b32_e32 v38, v226
	v_mov_b32_e32 v34, v227
	v_pk_mul_f32 v[36:37], v[30:31], v[38:39] op_sel_hi:[1,0]
	v_pk_mul_f32 v[38:39], v[32:33], v[38:39] op_sel_hi:[1,0]
	ds_write2_b32 v35, v36, v37 offset1:1
	ds_write2_b32 v35, v38, v39 offset0:2 offset1:3
	s_cbranch_execnz .LBB0_77

.LBB0_77:
	s_waitcnt vmcnt(6)
	v_pk_mul_f32 v[26:27], v[26:27], v[34:35] op_sel_hi:[1,0]
	v_add_u32_e32 v30, v80, v103
	ds_write2_b32 v30, v26, v27 offset1:1
	v_pk_mul_f32 v[26:27], v[28:29], v[34:35] op_sel_hi:[1,0]
	ds_write2_b32 v30, v26, v27 offset0:2 offset1:3
	s_and_b64 vcc, exec, s[4:5]
	v_add_u32_e32 v27, v80, v104
	s_cbranch_vccnz .LBB0_98
	s_ashr_i32 s31, s30, 31
	v_readlane_b32 s72, v254, 10
	v_lshl_add_u64 v[28:29], s[30:31], 0, v[68:69]
	v_readlane_b32 s82, v254, 20
	v_readlane_b32 s83, v254, 21
	v_readlane_b32 s73, v254, 11
	s_nop 0
	v_lshl_add_u64 v[28:29], v[28:29], 2, s[82:83]
	v_readlane_b32 s74, v254, 12
	v_readlane_b32 s75, v254, 13
	v_readlane_b32 s76, v254, 14
	v_readlane_b32 s77, v254, 15
	v_readlane_b32 s78, v254, 16
	v_readlane_b32 s79, v254, 17
	v_readlane_b32 s80, v254, 18
	v_readlane_b32 s81, v254, 19
	v_readlane_b32 s84, v254, 22
	v_readlane_b32 s85, v254, 23
	v_readlane_b32 s86, v254, 24
	v_readlane_b32 s87, v254, 25
	s_waitcnt vmcnt(4)
	v_mov_b32_e32 v30, v228
	v_mov_b32_e32 v26, v229
	v_pk_mul_f32 v[28:29], v[22:23], v[30:31] op_sel_hi:[1,0]
	v_pk_mul_f32 v[30:31], v[24:25], v[30:31] op_sel_hi:[1,0]
	ds_write2_b32 v27, v28, v29 offset1:1
	ds_write2_b32 v27, v30, v31 offset0:2 offset1:3
	s_cbranch_execnz .LBB0_80

.LBB0_80:
	s_waitcnt vmcnt(4)
	v_pk_mul_f32 v[18:19], v[18:19], v[26:27] op_sel_hi:[1,0]
	v_add_u32_e32 v22, 0x410, v27
	ds_write2_b32 v22, v18, v19 offset1:1
	v_pk_mul_f32 v[18:19], v[20:21], v[26:27] op_sel_hi:[1,0]
	v_add_u32_e32 v20, 0x418, v27
	ds_write2_b32 v20, v18, v19 offset1:1
	s_and_b64 vcc, exec, s[4:5]
	v_add_u32_e32 v19, 0x820, v27
	v_add_u32_e32 v20, 0x828, v27
	s_cbranch_vccnz .LBB0_99
	s_ashr_i32 s31, s30, 31
	v_readlane_b32 s72, v254, 10
	v_lshl_add_u64 v[22:23], s[30:31], 0, v[68:69]
	v_readlane_b32 s82, v254, 20
	v_readlane_b32 s83, v254, 21
	v_readlane_b32 s73, v254, 11
	s_nop 0
	v_lshl_add_u64 v[22:23], v[22:23], 2, s[82:83]
	v_readlane_b32 s74, v254, 12
	v_readlane_b32 s75, v254, 13
	v_readlane_b32 s76, v254, 14
	v_readlane_b32 s77, v254, 15
	v_readlane_b32 s78, v254, 16
	v_readlane_b32 s79, v254, 17
	v_readlane_b32 s80, v254, 18
	v_readlane_b32 s81, v254, 19
	v_readlane_b32 s84, v254, 22
	v_readlane_b32 s85, v254, 23
	v_readlane_b32 s86, v254, 24
	v_readlane_b32 s87, v254, 25
	s_waitcnt vmcnt(2)
	v_mov_b32_e32 v24, v230
	v_mov_b32_e32 v18, v231
	v_pk_mul_f32 v[22:23], v[14:15], v[24:25] op_sel_hi:[1,0]
	v_pk_mul_f32 v[24:25], v[16:17], v[24:25] op_sel_hi:[1,0]
	ds_write2_b32 v19, v22, v23 offset1:1
	ds_write2_b32 v20, v24, v25 offset1:1
	s_cbranch_execnz .LBB0_83

.LBB0_83:
	s_waitcnt vmcnt(2)
	v_pk_mul_f32 v[10:11], v[10:11], v[18:19] op_sel_hi:[1,0]
	v_add_u32_e32 v14, 0xc30, v27
	ds_write2_b32 v14, v10, v11 offset1:1
	v_pk_mul_f32 v[10:11], v[12:13], v[18:19] op_sel_hi:[1,0]
	v_add_u32_e32 v12, 0xc38, v27
	ds_write2_b32 v12, v10, v11 offset1:1
	s_and_b64 vcc, exec, s[4:5]
	v_add_u32_e32 v11, 0x1040, v27
	v_add_u32_e32 v12, 0x1048, v27
	s_cbranch_vccnz .LBB0_100
	s_ashr_i32 s31, s30, 31
	v_readlane_b32 s72, v254, 10
	v_lshl_add_u64 v[14:15], s[30:31], 0, v[68:69]
	v_readlane_b32 s82, v254, 20
	v_readlane_b32 s83, v254, 21
	v_readlane_b32 s73, v254, 11
	s_nop 0
	v_lshl_add_u64 v[14:15], v[14:15], 2, s[82:83]
	v_readlane_b32 s74, v254, 12
	v_readlane_b32 s75, v254, 13
	v_readlane_b32 s76, v254, 14
	v_readlane_b32 s77, v254, 15
	v_readlane_b32 s78, v254, 16
	v_readlane_b32 s79, v254, 17
	v_readlane_b32 s80, v254, 18
	v_readlane_b32 s81, v254, 19
	v_readlane_b32 s84, v254, 22
	v_readlane_b32 s85, v254, 23
	v_readlane_b32 s86, v254, 24
	v_readlane_b32 s87, v254, 25
	s_waitcnt vmcnt(0)
	v_mov_b32_e32 v16, v232
	v_mov_b32_e32 v10, v233
	v_pk_mul_f32 v[14:15], v[6:7], v[16:17] op_sel_hi:[1,0]
	v_pk_mul_f32 v[16:17], v[8:9], v[16:17] op_sel_hi:[1,0]
	ds_write2_b32 v11, v14, v15 offset1:1
	ds_write2_b32 v12, v16, v17 offset1:1
	s_cbranch_execnz .LBB0_33
	s_branch .LBB0_32
